# unpacked rescale plus running-max update threshold of 8 log2 units (rescale branch rarely taken; exact softmax identity, same dtypes)
# baseline (speedup 1.0000x reference)
.LBB0_459:
	ds_read_b64_tr_b16 v[188:189], v153 offset:9216
	ds_read_b64_tr_b16 v[190:191], v153 offset:9984
	ds_read_b64_tr_b16 v[192:193], v153 offset:9280
	ds_read_b64_tr_b16 v[194:195], v153 offset:10048
	ds_read_b64_tr_b16 v[196:197], v153 offset:12288
	ds_read_b64_tr_b16 v[198:199], v153 offset:13056
	ds_read_b64_tr_b16 v[200:201], v153 offset:12352
	ds_read_b64_tr_b16 v[202:203], v153 offset:13120
	ds_read_b64_tr_b16 v[204:205], v153 offset:15360
	ds_read_b64_tr_b16 v[206:207], v153 offset:16128
	ds_read_b64_tr_b16 v[208:209], v153 offset:15424
	ds_read_b64_tr_b16 v[210:211], v153 offset:16192
	ds_read_b64_tr_b16 v[212:213], v153 offset:18432
	ds_read_b64_tr_b16 v[214:215], v153 offset:19200
	ds_read_b64_tr_b16 v[216:217], v153 offset:18496
	ds_read_b64_tr_b16 v[218:219], v153 offset:19264
	s_nop 0
	v_max_f32_e32 v2, v147, v147
	s_nop 2
	v_max_f32_e32 v50, v146, v146
	v_max_f32_e32 v2, v50, v2
	v_max3_f32 v2, v2, v144, v145
	v_max3_f32 v2, v2, v142, v143
	v_max3_f32 v2, v2, v140, v141
	v_max3_f32 v2, v2, v138, v139
	v_max3_f32 v2, v2, v134, v135
	v_max3_f32 v2, v2, v130, v131
	v_max3_f32 v2, v2, v16, v17
	v_max3_f32 v2, v2, v136, v137
	v_max3_f32 v2, v2, v132, v133
	v_max3_f32 v2, v2, v14, v15
	v_max3_f32 v2, v2, v12, v13
	v_max3_f32 v2, v2, v10, v11
	v_max3_f32 v2, v2, v8, v9
	v_max3_f32 v2, v2, v6, v7
	v_max3_f32 v2, v2, v4, v5
	v_mov_b32_e32 v50, v2
	s_nop 1
	v_permlane32_swap_b32_e32 v50, v2
	v_max3_f32 v50, v173, v2, v50
	v_add_f32_e32 v2, 0x41000000, v173
	v_cmp_gt_f32_e32 vcc, v50, v2
	s_nop 1
	v_cndmask_b32_e32 v50, v173, v50, vcc
	v_sub_f32_e32 v2, v173, v50
	v_exp_f32_e32 v2, v2
	s_nop 0
	v_cmp_neq_f32_e32 vcc, 1.0, v2
	s_cbranch_vccz .LBB0_461
	v_mul_f32_e32 v48, v2, v48
	v_mul_f32_e32 v49, v2, v49
	v_mul_f32_e32 v46, v2, v46
	v_mul_f32_e32 v47, v2, v47
	v_mul_f32_e32 v44, v2, v44
	v_mul_f32_e32 v45, v2, v45
	v_mul_f32_e32 v42, v2, v42
	v_mul_f32_e32 v43, v2, v43
	v_mul_f32_e32 v40, v2, v40
	v_mul_f32_e32 v41, v2, v41
	v_mul_f32_e32 v38, v2, v38
	v_mul_f32_e32 v39, v2, v39
	v_mul_f32_e32 v36, v2, v36
	v_mul_f32_e32 v37, v2, v37
	v_mul_f32_e32 v34, v2, v34
	v_mul_f32_e32 v35, v2, v35
	v_mul_f32_e32 v32, v2, v32
	v_mul_f32_e32 v33, v2, v33
	v_mul_f32_e32 v30, v2, v30
	v_mul_f32_e32 v31, v2, v31
	v_mul_f32_e32 v28, v2, v28
	v_mul_f32_e32 v29, v2, v29
	v_mul_f32_e32 v26, v2, v26
	v_mul_f32_e32 v27, v2, v27
	v_mul_f32_e32 v24, v2, v24
	v_mul_f32_e32 v25, v2, v25
	v_mul_f32_e32 v22, v2, v22
	v_mul_f32_e32 v23, v2, v23
	v_mul_f32_e32 v20, v2, v20
	v_mul_f32_e32 v21, v2, v21
	v_mul_f32_e32 v18, v2, v18
	v_mul_f32_e32 v19, v2, v19

.LBB0_1611:
	v_lshl_add_u64 v[66:67], v[214:215], 0, s[56:57]
	v_cndmask_b32_e64 v67, v217, v67, s[4:5]
	v_cndmask_b32_e64 v66, v216, v66, s[4:5]
	s_waitcnt vmcnt(63) expcnt(7) lgkmcnt(15)
	s_barrier
	s_waitcnt vmcnt(4)
	ds_write_b128 v229, v[146:149]
	s_waitcnt vmcnt(3)
	ds_write_b128 v230, v[150:153]
	s_waitcnt vmcnt(2)
	ds_write_b128 v231, v[154:157]
	s_waitcnt vmcnt(1)
	ds_write_b128 v232, v[162:165] offset:25600
	s_waitcnt vmcnt(0)
	ds_write_b128 v233, v[158:161] offset:25600
	s_waitcnt lgkmcnt(0)
	s_barrier
	global_load_dwordx4 v[146:149], v[66:67], off
	v_lshl_add_u64 v[66:67], v[210:211], 0, s[56:57]
	v_cndmask_b32_e64 v67, v213, v67, s[8:9]
	v_cndmask_b32_e64 v66, v212, v66, s[8:9]
	global_load_dwordx4 v[150:153], v[66:67], off
	v_lshl_add_u64 v[66:67], v[206:207], 0, s[56:57]
	v_cndmask_b32_e64 v67, v209, v67, s[12:13]
	v_cndmask_b32_e64 v66, v208, v66, s[12:13]
	global_load_dwordx4 v[154:157], v[66:67], off
	v_lshl_add_u64 v[66:67], v[204:205], 0, s[56:57]
	v_lshl_add_u64 v[68:69], v[202:203], 0, s[56:57]
	global_load_dwordx4 v[162:165], v[66:67], off
	global_load_dwordx4 v[158:161], v[68:69], off
	s_cmp_gt_i32 s58, s29
	s_cbranch_scc1 .LBB0_1615
	v_add_u32_e32 v235, v226, v225
	ds_read_b128 v[66:69], v235
	ds_read_b128 v[236:239], v235 offset:32
	ds_read_b128 v[70:73], v235 offset:12800
	ds_read_b128 v[244:247], v235 offset:12832
	s_waitcnt lgkmcnt(3)
	v_mfma_f32_32x32x16_bf16 v[82:97], v[66:69], v[142:145], 0
	ds_read_b128 v[248:251], v235 offset:64
	ds_read_b128 v[252:255], v235 offset:12864
	s_waitcnt lgkmcnt(3)
	v_mfma_f32_32x32x16_bf16 v[66:81], v[70:73], v[142:145], 0
	v_mfma_f32_32x32x16_bf16 v[82:97], v[236:239], v[138:141], v[82:97]
	s_waitcnt lgkmcnt(2)
	v_mfma_f32_32x32x16_bf16 v[66:81], v[244:247], v[138:141], v[66:81]
	ds_read_b128 v[236:239], v235 offset:96
	ds_read_b128 v[244:247], v235 offset:12896
	s_waitcnt lgkmcnt(3)
	v_mfma_f32_32x32x16_bf16 v[82:97], v[248:251], v[134:137], v[82:97]
	s_waitcnt lgkmcnt(2)
	v_mfma_f32_32x32x16_bf16 v[66:81], v[252:255], v[134:137], v[66:81]
	ds_read_b128 v[248:251], v235 offset:128
	ds_read_b128 v[252:255], v235 offset:12928
	s_waitcnt lgkmcnt(3)
	v_mfma_f32_32x32x16_bf16 v[82:97], v[236:239], v[130:133], v[82:97]
	s_waitcnt lgkmcnt(2)
	v_mfma_f32_32x32x16_bf16 v[66:81], v[244:247], v[130:133], v[66:81]
	ds_read_b128 v[236:239], v235 offset:160
	ds_read_b128 v[244:247], v235 offset:12960
	s_waitcnt lgkmcnt(3)
	v_mfma_f32_32x32x16_bf16 v[82:97], v[248:251], v[126:129], v[82:97]
	s_waitcnt lgkmcnt(2)
	v_mfma_f32_32x32x16_bf16 v[66:81], v[252:255], v[126:129], v[66:81]
	ds_read_b128 v[248:251], v235 offset:192
	ds_read_b128 v[252:255], v235 offset:12992
	s_waitcnt lgkmcnt(3)
	v_mfma_f32_32x32x16_bf16 v[82:97], v[236:239], v[122:125], v[82:97]
	s_waitcnt lgkmcnt(2)
	v_mfma_f32_32x32x16_bf16 v[66:81], v[244:247], v[122:125], v[66:81]
	ds_read_b128 v[236:239], v235 offset:224
	ds_read_b128 v[244:247], v235 offset:13024
	s_waitcnt lgkmcnt(3)
	v_mfma_f32_32x32x16_bf16 v[82:97], v[248:251], v[118:121], v[82:97]
	s_waitcnt lgkmcnt(2)
	v_mfma_f32_32x32x16_bf16 v[66:81], v[252:255], v[118:121], v[66:81]
	ds_read_b128 v[248:251], v235 offset:256
	ds_read_b128 v[252:255], v235 offset:13056
	s_waitcnt lgkmcnt(3)
	v_mfma_f32_32x32x16_bf16 v[82:97], v[236:239], v[114:117], v[82:97]
	s_waitcnt lgkmcnt(2)
	v_mfma_f32_32x32x16_bf16 v[66:81], v[244:247], v[114:117], v[66:81]
	ds_read_b128 v[236:239], v235 offset:288
	ds_read_b128 v[244:247], v235 offset:13088
	s_waitcnt lgkmcnt(3)
	v_mfma_f32_32x32x16_bf16 v[82:97], v[248:251], v[110:113], v[82:97]
	s_waitcnt lgkmcnt(2)
	v_mfma_f32_32x32x16_bf16 v[66:81], v[252:255], v[110:113], v[66:81]
	ds_read_b128 v[248:251], v235 offset:320
	ds_read_b128 v[252:255], v235 offset:13120
	s_waitcnt lgkmcnt(3)
	v_mfma_f32_32x32x16_bf16 v[82:97], v[236:239], v[106:109], v[82:97]
	s_waitcnt lgkmcnt(2)
	v_mfma_f32_32x32x16_bf16 v[66:81], v[244:247], v[106:109], v[66:81]
	ds_read_b128 v[236:239], v235 offset:352
	ds_read_b128 v[244:247], v235 offset:13152
	s_waitcnt lgkmcnt(3)
	v_mfma_f32_32x32x16_bf16 v[82:97], v[248:251], v[102:105], v[82:97]
	s_waitcnt lgkmcnt(2)
	v_mfma_f32_32x32x16_bf16 v[66:81], v[252:255], v[102:105], v[66:81]
	s_waitcnt lgkmcnt(1)
	v_mfma_f32_32x32x16_bf16 v[82:97], v[236:239], v[98:101], v[82:97]
	s_waitcnt lgkmcnt(0)
	v_mfma_f32_32x32x16_bf16 v[66:81], v[244:247], v[98:101], v[66:81]
	s_nop 9
	v_max_f32_e32 v235, v83, v83
	v_max_f32_e32 v236, v82, v82
	v_max_f32_e32 v235, v236, v235
	v_max3_f32 v235, v235, v84, v85
	v_max3_f32 v235, v235, v86, v87
	v_max3_f32 v235, v235, v88, v89
	v_max3_f32 v235, v235, v90, v91
	v_max3_f32 v235, v235, v92, v93
	v_max3_f32 v235, v235, v94, v95
	v_max3_f32 v235, v235, v96, v97
	v_max3_f32 v235, v235, v66, v67
	v_max3_f32 v235, v235, v68, v69
	v_max3_f32 v235, v235, v70, v71
	v_max3_f32 v235, v235, v72, v73
	v_max3_f32 v235, v235, v74, v75
	v_max3_f32 v235, v235, v76, v77
	v_max3_f32 v235, v235, v78, v79
	v_max3_f32 v235, v235, v80, v81
	v_mov_b32_e32 v236, v235
	s_nop 1
	v_permlane32_swap_b32_e32 v236, v235
	s_waitcnt lgkmcnt(0)
	v_max3_f32 v235, v218, v235, v236
	v_add_f32_e32 v236, 0x41000000, v218
	v_cmp_gt_f32_e32 vcc, v235, v236
	s_nop 1
	v_cndmask_b32_e32 v235, v218, v235, vcc
	v_sub_f32_e32 v218, v218, v235
	v_exp_f32_e32 v218, v218
	s_nop 0
	v_cmp_neq_f32_e32 vcc, 1.0, v218
	s_cbranch_vccz .LBB0_1614
	v_mul_f32_e32 v64, v218, v64
	v_mul_f32_e32 v65, v218, v65
	v_mul_f32_e32 v62, v218, v62
	v_mul_f32_e32 v63, v218, v63
	v_mul_f32_e32 v60, v218, v60
	v_mul_f32_e32 v61, v218, v61
	v_mul_f32_e32 v58, v218, v58
	v_mul_f32_e32 v59, v218, v59
	v_mul_f32_e32 v56, v218, v56
	v_mul_f32_e32 v57, v218, v57
	v_mul_f32_e32 v54, v218, v54
	v_mul_f32_e32 v55, v218, v55
	v_mul_f32_e32 v52, v218, v52
	v_mul_f32_e32 v53, v218, v53
	v_mul_f32_e32 v50, v218, v50
	v_mul_f32_e32 v51, v218, v51
	v_mul_f32_e32 v48, v218, v48
	v_mul_f32_e32 v49, v218, v49
	v_mul_f32_e32 v46, v218, v46
	v_mul_f32_e32 v47, v218, v47
	v_mul_f32_e32 v44, v218, v44
	v_mul_f32_e32 v45, v218, v45
	v_mul_f32_e32 v42, v218, v42
	v_mul_f32_e32 v43, v218, v43
	v_mul_f32_e32 v40, v218, v40
	v_mul_f32_e32 v41, v218, v41
	v_mul_f32_e32 v38, v218, v38
	v_mul_f32_e32 v39, v218, v39
	v_mul_f32_e32 v36, v218, v36
	v_mul_f32_e32 v37, v218, v37
	v_mul_f32_e32 v34, v218, v34
	v_mul_f32_e32 v35, v218, v35
	v_mul_f32_e32 v32, v218, v32
	v_mul_f32_e32 v33, v218, v33
	v_mul_f32_e32 v30, v218, v30
	v_mul_f32_e32 v31, v218, v31
	v_mul_f32_e32 v28, v218, v28
	v_mul_f32_e32 v29, v218, v29
	v_mul_f32_e32 v26, v218, v26
	v_mul_f32_e32 v27, v218, v27
	v_mul_f32_e32 v24, v218, v24
	v_mul_f32_e32 v25, v218, v25
	v_mul_f32_e32 v22, v218, v22
	v_mul_f32_e32 v23, v218, v23
	v_mul_f32_e32 v20, v218, v20
	v_mul_f32_e32 v21, v218, v21
	v_mul_f32_e32 v18, v218, v18
	v_mul_f32_e32 v19, v218, v19
	v_mul_f32_e32 v16, v218, v16
	v_mul_f32_e32 v17, v218, v17
	v_mul_f32_e32 v14, v218, v14
	v_mul_f32_e32 v15, v218, v15
	v_mul_f32_e32 v12, v218, v12
	v_mul_f32_e32 v13, v218, v13
	v_mul_f32_e32 v10, v218, v10
	v_mul_f32_e32 v11, v218, v11
	v_mul_f32_e32 v8, v218, v8
	v_mul_f32_e32 v9, v218, v9
	v_mul_f32_e32 v6, v218, v6
	v_mul_f32_e32 v7, v218, v7
	v_mul_f32_e32 v4, v218, v4
	v_mul_f32_e32 v5, v218, v5
	v_mul_f32_e32 v2, v218, v2
	v_mul_f32_e32 v3, v218, v3

.LBB0_1618:
	s_andn2_b64 vcc, exec, s[48:49]
	s_barrier
	s_waitcnt vmcnt(4)
	ds_write_b128 v229, v[146:149]
	s_waitcnt vmcnt(3)
	ds_write_b128 v230, v[150:153]
	s_waitcnt vmcnt(2)
	ds_write_b128 v231, v[154:157]
	s_waitcnt vmcnt(1)
	ds_write_b128 v232, v[162:165] offset:25600
	s_waitcnt vmcnt(0)
	ds_write_b128 v233, v[158:161] offset:25600
	s_waitcnt lgkmcnt(0)
	s_barrier
	s_cbranch_vccnz .LBB0_1597
	v_add_u32_e32 v162, v226, v225
	ds_read_b128 v[66:69], v162
	ds_read_b128 v[146:149], v162 offset:32
	ds_read_b128 v[70:73], v162 offset:12800
	ds_read_b128 v[150:153], v162 offset:12832
	s_waitcnt lgkmcnt(3)
	v_mfma_f32_32x32x16_bf16 v[82:97], v[66:69], v[142:145], 0
	ds_read_b128 v[154:157], v162 offset:64
	ds_read_b128 v[158:161], v162 offset:12864
	s_waitcnt lgkmcnt(3)
	v_mfma_f32_32x32x16_bf16 v[66:81], v[70:73], v[142:145], 0
	v_mfma_f32_32x32x16_bf16 v[82:97], v[146:149], v[138:141], v[82:97]
	ds_read_b128 v[142:145], v162 offset:96
	ds_read_b128 v[146:149], v162 offset:12896
	s_waitcnt lgkmcnt(4)
	v_mfma_f32_32x32x16_bf16 v[66:81], v[150:153], v[138:141], v[66:81]
	s_waitcnt lgkmcnt(3)
	v_mfma_f32_32x32x16_bf16 v[82:97], v[154:157], v[134:137], v[82:97]
	ds_read_b128 v[138:141], v162 offset:128
	ds_read_b128 v[150:153], v162 offset:12928
	s_waitcnt lgkmcnt(4)
	v_mfma_f32_32x32x16_bf16 v[66:81], v[158:161], v[134:137], v[66:81]
	s_waitcnt lgkmcnt(3)
	v_mfma_f32_32x32x16_bf16 v[82:97], v[142:145], v[130:133], v[82:97]
	ds_read_b128 v[134:137], v162 offset:160
	ds_read_b128 v[142:145], v162 offset:12960
	s_waitcnt lgkmcnt(4)
	v_mfma_f32_32x32x16_bf16 v[66:81], v[146:149], v[130:133], v[66:81]
	s_waitcnt lgkmcnt(3)
	v_mfma_f32_32x32x16_bf16 v[82:97], v[138:141], v[126:129], v[82:97]
	ds_read_b128 v[130:133], v162 offset:192
	ds_read_b128 v[138:141], v162 offset:12992
	s_waitcnt lgkmcnt(4)
	v_mfma_f32_32x32x16_bf16 v[66:81], v[150:153], v[126:129], v[66:81]
	s_waitcnt lgkmcnt(3)
	v_mfma_f32_32x32x16_bf16 v[82:97], v[134:137], v[122:125], v[82:97]
	ds_read_b128 v[126:129], v162 offset:224
	ds_read_b128 v[134:137], v162 offset:13024
	s_waitcnt lgkmcnt(4)
	v_mfma_f32_32x32x16_bf16 v[66:81], v[142:145], v[122:125], v[66:81]
	s_waitcnt lgkmcnt(3)
	v_mfma_f32_32x32x16_bf16 v[82:97], v[130:133], v[118:121], v[82:97]
	ds_read_b128 v[122:125], v162 offset:256
	ds_read_b128 v[130:133], v162 offset:13056
	s_waitcnt lgkmcnt(4)
	v_mfma_f32_32x32x16_bf16 v[66:81], v[138:141], v[118:121], v[66:81]
	s_waitcnt lgkmcnt(3)
	v_mfma_f32_32x32x16_bf16 v[82:97], v[126:129], v[114:117], v[82:97]
	ds_read_b128 v[118:121], v162 offset:288
	ds_read_b128 v[126:129], v162 offset:13088
	s_waitcnt lgkmcnt(4)
	v_mfma_f32_32x32x16_bf16 v[66:81], v[134:137], v[114:117], v[66:81]
	s_waitcnt lgkmcnt(3)
	v_mfma_f32_32x32x16_bf16 v[82:97], v[122:125], v[110:113], v[82:97]
	ds_read_b128 v[114:117], v162 offset:320
	ds_read_b128 v[122:125], v162 offset:13120
	s_waitcnt lgkmcnt(4)
	v_mfma_f32_32x32x16_bf16 v[66:81], v[130:133], v[110:113], v[66:81]
	s_waitcnt lgkmcnt(3)
	v_mfma_f32_32x32x16_bf16 v[82:97], v[118:121], v[106:109], v[82:97]
	ds_read_b128 v[110:113], v162 offset:352
	ds_read_b128 v[118:121], v162 offset:13152
	s_waitcnt lgkmcnt(4)
	v_mfma_f32_32x32x16_bf16 v[66:81], v[126:129], v[106:109], v[66:81]
	s_waitcnt lgkmcnt(3)
	v_mfma_f32_32x32x16_bf16 v[82:97], v[114:117], v[102:105], v[82:97]
	s_waitcnt lgkmcnt(2)
	v_mfma_f32_32x32x16_bf16 v[66:81], v[122:125], v[102:105], v[66:81]
	s_waitcnt lgkmcnt(1)
	v_mfma_f32_32x32x16_bf16 v[82:97], v[110:113], v[98:101], v[82:97]
	s_waitcnt lgkmcnt(0)
	v_mfma_f32_32x32x16_bf16 v[66:81], v[118:121], v[98:101], v[66:81]
	s_nop 9
	v_max_f32_e32 v98, v83, v83
	v_max_f32_e32 v99, v82, v82
	v_max_f32_e32 v98, v99, v98
	v_max3_f32 v98, v98, v84, v85
	v_max3_f32 v98, v98, v86, v87
	v_max3_f32 v98, v98, v88, v89
	v_max3_f32 v98, v98, v90, v91
	v_max3_f32 v98, v98, v92, v93
	v_max3_f32 v98, v98, v94, v95
	v_max3_f32 v98, v98, v96, v97
	v_max3_f32 v98, v98, v66, v67
	v_max3_f32 v98, v98, v68, v69
	v_max3_f32 v98, v98, v70, v71
	v_max3_f32 v98, v98, v72, v73
	v_max3_f32 v98, v98, v74, v75
	v_max3_f32 v98, v98, v76, v77
	v_max3_f32 v98, v98, v78, v79
	v_max3_f32 v98, v98, v80, v81
	v_mov_b32_e32 v99, v98
	s_nop 1
	v_permlane32_swap_b32_e32 v99, v98
	s_waitcnt lgkmcnt(0)
	v_max3_f32 v99, v235, v98, v99
	v_add_f32_e32 v98, 0x41000000, v235
	v_cmp_gt_f32_e32 vcc, v99, v98
	s_nop 1
	v_cndmask_b32_e32 v99, v235, v99, vcc
	v_sub_f32_e32 v98, v235, v99
	v_exp_f32_e32 v98, v98
	s_nop 0
	v_cmp_neq_f32_e32 vcc, 1.0, v98
	s_cbranch_vccz .LBB0_1596
	v_mul_f32_e32 v64, v98, v64
	v_mul_f32_e32 v65, v98, v65
	v_mul_f32_e32 v62, v98, v62
	v_mul_f32_e32 v63, v98, v63
	v_mul_f32_e32 v60, v98, v60
	v_mul_f32_e32 v61, v98, v61
	v_mul_f32_e32 v58, v98, v58
	v_mul_f32_e32 v59, v98, v59
	v_mul_f32_e32 v56, v98, v56
	v_mul_f32_e32 v57, v98, v57
	v_mul_f32_e32 v54, v98, v54
	v_mul_f32_e32 v55, v98, v55
	v_mul_f32_e32 v52, v98, v52
	v_mul_f32_e32 v53, v98, v53
	v_mul_f32_e32 v50, v98, v50
	v_mul_f32_e32 v51, v98, v51
	v_mul_f32_e32 v48, v98, v48
	v_mul_f32_e32 v49, v98, v49
	v_mul_f32_e32 v46, v98, v46
	v_mul_f32_e32 v47, v98, v47
	v_mul_f32_e32 v44, v98, v44
	v_mul_f32_e32 v45, v98, v45
	v_mul_f32_e32 v42, v98, v42
	v_mul_f32_e32 v43, v98, v43
	v_mul_f32_e32 v40, v98, v40
	v_mul_f32_e32 v41, v98, v41
	v_mul_f32_e32 v38, v98, v38
	v_mul_f32_e32 v39, v98, v39
	v_mul_f32_e32 v36, v98, v36
	v_mul_f32_e32 v37, v98, v37
	v_mul_f32_e32 v34, v98, v34
	v_mul_f32_e32 v35, v98, v35
	v_mul_f32_e32 v32, v98, v32
	v_mul_f32_e32 v33, v98, v33
	v_mul_f32_e32 v30, v98, v30
	v_mul_f32_e32 v31, v98, v31
	v_mul_f32_e32 v28, v98, v28
	v_mul_f32_e32 v29, v98, v29
	v_mul_f32_e32 v26, v98, v26
	v_mul_f32_e32 v27, v98, v27
	v_mul_f32_e32 v24, v98, v24
	v_mul_f32_e32 v25, v98, v25
	v_mul_f32_e32 v22, v98, v22
	v_mul_f32_e32 v23, v98, v23
	v_mul_f32_e32 v20, v98, v20
	v_mul_f32_e32 v21, v98, v21
	v_mul_f32_e32 v18, v98, v18
	v_mul_f32_e32 v19, v98, v19
	v_mul_f32_e32 v16, v98, v16
	v_mul_f32_e32 v17, v98, v17
	v_mul_f32_e32 v14, v98, v14
	v_mul_f32_e32 v15, v98, v15
	v_mul_f32_e32 v12, v98, v12
	v_mul_f32_e32 v13, v98, v13
	v_mul_f32_e32 v10, v98, v10
	v_mul_f32_e32 v11, v98, v11
	v_mul_f32_e32 v8, v98, v8
	v_mul_f32_e32 v9, v98, v9
	v_mul_f32_e32 v6, v98, v6
	v_mul_f32_e32 v7, v98, v7
	v_mul_f32_e32 v4, v98, v4
	v_mul_f32_e32 v5, v98, v5
	v_mul_f32_e32 v2, v98, v2
	v_mul_f32_e32 v3, v98, v3
	s_branch .LBB0_1596
